# prompt attention: one static s_setprio 1 for waves 0-3 (the older half) for the whole attention section, reset at its exit
# speedup vs baseline: 1.0057x; 1.0057x over previous
; template<int THRL,bool PART> __device__ __forceinline__ int attn_unit(const bf16*Qb,const bf16*__restrict__ Kh,const bf16*__restrict__ Vh,bf16*Ob,const int NT,const int vlim_in,char*shm,const int s0,const bool primed,const bf16*nKh,const bf16*nVh,bf16*fuseM,const float lam){
;   int tid=threadIdx.x; asm volatile("":"+v"(tid));
;   const int lane=tid&63,r32=lane&31,hi=lane>>5; const int wid=__builtin_amdgcn_readfirstlane(tid>>6);
;   const int vlim=(vlim_in<0)?(wid>>1):vlim_in;
;   const bool act=PART?(wid<2):true;
; __global__ void __launch_bounds__(NWAVES * 64, 2) mk_fwd(Args args) {
;     ...
;     if (IN(7)) { __syncthreads();
;         { const float lam = MISC[0];
;         for (int v = vcu; v < 256; v += G) {
.LBB0_925:
	s_cmpk_gt_i32 s92, 0xff
	s_waitcnt vmcnt(0) lgkmcnt(0)
	s_barrier
	s_cbranch_scc1 .LBB0_1021
	v_mov_b32_e32 v3, 0x1a0000
	global_load_dword v217, v3, s[66:67]
	v_and_b32_e32 v0, 63, v252
	v_and_b32_e32 v1, 31, v252
	v_bfe_u32 v2, v252, 5, 1
	v_lshrrev_b32_e32 v3, 6, v252
	s_nop 0
	v_readfirstlane_b32 s4, v3
	s_and_b32 s5, s4, 3
	s_lshr_b32 s6, s4, 2
	s_mov_b32 s48, 0x41000000
	s_xor_b32 s45, s4, 2
	s_cmp_lt_u32 s4, 4
	s_cselect_b32 s45, s4, s45
	s_and_b32 s46, s45, 3
	s_lshr_b32 s47, s45, 2
	s_cmp_ge_u32 s4, 4
	s_cbranch_scc1 .Lat_prio
	s_setprio 1
